# P2 rope epilogue (pn==16 tiles): preload the wave's 16 rope-table entries before the first step, steps no longer wait vmcnt(0) behind the previous step's stores
# speedup vs baseline: 1.0062x; 1.0062x over previous
.LBB0_177:
	s_lshl_b32 s87, s8, 8
	s_lshl_b32 s86, s14, 8
	s_cmp_gt_i32 s14, 3
	s_mov_b64 s[4:5], -1
	s_cbranch_scc0 .LBB0_229
	s_and_b32 s14, s14, 0xffff
	s_cmp_gt_u32 s14, 11
	s_cbranch_scc0 .LBB0_441
	s_cmp_gt_u32 s14, 15
	s_cbranch_scc0 .LBB0_438
	v_add_u32_e32 v140, s87, v154
	v_add_u32_e32 v132, 0xffffe000, v140
	v_mov_b32_e32 v133, v129
	v_lshrrev_b32_e32 v131, 5, v132
	v_lshlrev_b64 v[134:135], 8, v[132:133]
	v_ashrrev_i32_e32 v141, 31, v140
	v_mad_u64_u32 v[132:133], s[0:1], v131, s66, 0
	v_lshlrev_b64 v[138:139], 7, v[140:141]
	v_or_b32_e32 v132, v132, v155
	s_mov_b64 s[0:1], 0x1000
	v_lshl_add_u64 v[146:147], s[64:65], 0, v[138:139]
	v_lshl_add_u64 v[132:133], v[132:133], 0, s[0:1]
	v_mov_b64_e32 v[138:139], s[50:51]
	v_lshl_or_b32 v128, v153, 2, s33
	v_mad_u64_u32 v[138:139], s[0:1], v132, s67, v[138:139]
	v_or_b32_e32 v130, s86, v128
	v_and_b32_e32 v128, 0xfcf, v140
	v_or_b32_e32 v158, 0x1000, v155
	v_cmp_gt_i32_e32 vcc, s23, v140
	v_lshlrev_b64 v[136:137], 8, v[140:141]
	v_mad_u32_u24 v139, v133, s67, v139
	s_mov_b64 s[0:1], 0x131edb00
	v_cndmask_b32_e32 v128, v158, v128, vcc
	v_lshl_add_u64 v[134:135], s[30:31], 0, v[134:135]
	v_lshl_add_u64 v[136:137], s[58:59], 0, v[136:137]
	v_lshl_add_u64 v[142:143], v[138:139], 0, s[0:1]
	s_mov_b64 s[0:1], 0x131edb40
	v_add_u32_e32 v131, 0xfffff000, v130
	v_lshlrev_b32_e32 v128, 5, v128
	v_cmp_lt_i32_e64 s[12:13], s56, v140
	v_lshl_add_u64 v[144:145], v[138:139], 0, s[0:1]
	v_cmp_gt_i32_e64 s[4:5], s66, v130
	v_ashrrev_i32_e32 v132, 1, v131
	v_cndmask_b32_e32 v149, v135, v137, vcc
	v_cndmask_b32_e32 v148, v134, v136, vcc
	s_mov_b64 s[98:99], exec
	s_and_b64 exec, exec, s[4:5]
	s_cbranch_execz .Lp2rope_done
	s_movk_i32 s100, 0xfff
	s_mov_b32 s101, 0
	s_cmpk_lt_u32 s87, 0x2000
	s_cbranch_scc1 .Lp2rope_prm
	s_movk_i32 s100, 31
	s_movk_i32 s101, 0x1000
.Lp2rope_prm:
	v_mov_b32_e32 v236, v140
	v_and_b32_e32 v236, s100, v236
	v_or_b32_e32 v236, s101, v236
	v_lshl_add_u32 v236, v236, 5, v132
	v_lshlrev_b32_e32 v236, 3, v236
	global_load_dwordx4 v[172:175], v236, s[16:17]
	global_load_dwordx4 v[176:179], v236, s[16:17] offset:64
	v_add_u32_e32 v236, 0x10, v140
	v_and_b32_e32 v236, s100, v236
	v_or_b32_e32 v236, s101, v236
	v_lshl_add_u32 v236, v236, 5, v132
	v_lshlrev_b32_e32 v236, 3, v236
	global_load_dwordx4 v[180:183], v236, s[16:17]
	global_load_dwordx4 v[184:187], v236, s[16:17] offset:64
	v_add_u32_e32 v236, 0x20, v140
	v_and_b32_e32 v236, s100, v236
	v_or_b32_e32 v236, s101, v236
	v_lshl_add_u32 v236, v236, 5, v132
	v_lshlrev_b32_e32 v236, 3, v236
	global_load_dwordx4 v[188:191], v236, s[16:17]
	global_load_dwordx4 v[192:195], v236, s[16:17] offset:64
	v_add_u32_e32 v236, 0x30, v140
	v_and_b32_e32 v236, s100, v236
	v_or_b32_e32 v236, s101, v236
	v_lshl_add_u32 v236, v236, 5, v132
	v_lshlrev_b32_e32 v236, 3, v236
	global_load_dwordx4 v[196:199], v236, s[16:17]
	global_load_dwordx4 v[200:203], v236, s[16:17] offset:64
	v_add_u32_e32 v236, 0x80, v140
	v_and_b32_e32 v236, s100, v236
	v_or_b32_e32 v236, s101, v236
	v_lshl_add_u32 v236, v236, 5, v132
	v_lshlrev_b32_e32 v236, 3, v236
	global_load_dwordx4 v[204:207], v236, s[16:17]
	global_load_dwordx4 v[208:211], v236, s[16:17] offset:64
	v_add_u32_e32 v236, 0x90, v140
	v_and_b32_e32 v236, s100, v236
	v_or_b32_e32 v236, s101, v236
	v_lshl_add_u32 v236, v236, 5, v132
	v_lshlrev_b32_e32 v236, 3, v236
	global_load_dwordx4 v[212:215], v236, s[16:17]
	global_load_dwordx4 v[216:219], v236, s[16:17] offset:64
	v_add_u32_e32 v236, 0xa0, v140
	v_and_b32_e32 v236, s100, v236
	v_or_b32_e32 v236, s101, v236
	v_lshl_add_u32 v236, v236, 5, v132
	v_lshlrev_b32_e32 v236, 3, v236
	global_load_dwordx4 v[220:223], v236, s[16:17]
	global_load_dwordx4 v[224:227], v236, s[16:17] offset:64
	v_add_u32_e32 v236, 0xb0, v140
	v_and_b32_e32 v236, s100, v236
	v_or_b32_e32 v236, s101, v236
	v_lshl_add_u32 v236, v236, 5, v132
	v_lshlrev_b32_e32 v236, 3, v236
	global_load_dwordx4 v[228:231], v236, s[16:17]
	global_load_dwordx4 v[232:235], v236, s[16:17] offset:64
.Lp2rope_done:
	s_mov_b64 exec, s[98:99]
	s_and_saveexec_b64 s[0:1], s[4:5]
	s_xor_b64 s[6:7], exec, s[0:1]
	s_cbranch_execz .LBB0_184
	v_ashrrev_i32_e32 v133, 31, v132
	v_lshl_add_u64 v[134:135], v[132:133], 0, v[128:129]
	v_lshl_add_u64 v[134:135], v[134:135], 3, s[16:17]
	s_waitcnt vmcnt(0)
	v_mov_b64_e32 v[134:135], v[172:173]
	v_mov_b64_e32 v[136:137], v[174:175]
	v_mov_b32_e32 v160, v120
	v_mov_b32_e32 v161, v123
	v_pk_mul_f32 v[138:139], v[122:123], v[136:137]
	v_pk_mul_f32 v[150:151], v[120:121], v[134:135]
	v_mov_b32_e32 v157, v138
	v_mov_b32_e32 v156, v150
	v_mov_b32_e32 v138, v151
	v_pk_add_f32 v[138:139], v[156:157], v[138:139] neg_lo:[0,1] neg_hi:[0,1]
	v_mov_b32_e32 v156, v134
	v_mov_b32_e32 v134, v135
	v_mov_b32_e32 v135, v136
	v_mov_b32_e32 v150, v121
	v_mov_b32_e32 v151, v122
	v_mov_b32_e32 v157, v137
	v_pk_mul_f32 v[134:135], v[160:161], v[134:135]
	v_lshl_add_u64 v[136:137], v[132:133], 2, v[148:149]
	v_pk_fma_f32 v[134:135], v[150:151], v[156:157], v[134:135]
	global_store_dwordx2 v[136:137], v[138:139], off
	global_store_dwordx2 v[136:137], v[134:135], off offset:128
	v_cvt_pk_bf16_f32 v131, v138, v139
	v_cvt_pk_bf16_f32 v134, v134, v135
	v_lshl_add_u64 v[136:137], v[132:133], 1, v[146:147]
	global_store_dword v[136:137], v131, off
	global_store_dword v[136:137], v134, off offset:64
	s_and_saveexec_b64 s[8:9], s[12:13]
	s_cbranch_execz .LBB0_183
	v_lshlrev_b64 v[136:137], 1, v[132:133]
	v_lshl_add_u64 v[138:139], v[142:143], 0, v[136:137]
	v_lshl_add_u64 v[136:137], v[144:145], 0, v[136:137]
	global_store_dword v[138:139], v131, off
	global_store_dword v[136:137], v134, off

.LBB0_188:
	s_or_b64 exec, exec, s[6:7]
	v_or_b32_e32 v131, 16, v130
	v_cmp_gt_i32_e64 s[6:7], s66, v131
	v_add_u32_e32 v131, 0xfffff010, v130
	v_ashrrev_i32_e32 v134, 1, v131
	s_and_saveexec_b64 s[0:1], s[6:7]
	s_xor_b64 s[8:9], exec, s[0:1]
	s_cbranch_execz .LBB0_192
	v_ashrrev_i32_e32 v135, 31, v134
	v_lshl_add_u64 v[136:137], v[134:135], 0, v[128:129]
	v_lshl_add_u64 v[136:137], v[136:137], 3, s[16:17]
	v_mov_b64_e32 v[136:137], v[176:177]
	v_mov_b64_e32 v[138:139], v[178:179]
	v_mov_b32_e32 v164, v112
	v_mov_b32_e32 v165, v115
	v_pk_mul_f32 v[156:157], v[114:115], v[138:139]
	v_pk_mul_f32 v[160:161], v[112:113], v[136:137]
	v_mov_b32_e32 v163, v156
	v_mov_b32_e32 v162, v160
	v_mov_b32_e32 v156, v161
	v_pk_add_f32 v[156:157], v[162:163], v[156:157] neg_lo:[0,1] neg_hi:[0,1]
	v_mov_b32_e32 v162, v136
	v_mov_b32_e32 v136, v137
	v_mov_b32_e32 v137, v138
	v_mov_b32_e32 v160, v113
	v_mov_b32_e32 v161, v114
	v_mov_b32_e32 v163, v139
	v_pk_mul_f32 v[136:137], v[164:165], v[136:137]
	v_lshl_add_u64 v[138:139], v[134:135], 2, v[148:149]
	v_pk_fma_f32 v[136:137], v[160:161], v[162:163], v[136:137]
	global_store_dwordx2 v[138:139], v[156:157], off
	global_store_dwordx2 v[138:139], v[136:137], off offset:128
	v_cvt_pk_bf16_f32 v131, v156, v157
	v_cvt_pk_bf16_f32 v133, v136, v137
	v_lshl_add_u64 v[136:137], v[134:135], 1, v[146:147]
	global_store_dword v[136:137], v131, off
	global_store_dword v[136:137], v133, off offset:64
	s_and_saveexec_b64 s[10:11], s[12:13]
	s_cbranch_execz .LBB0_191
	v_lshlrev_b64 v[136:137], 1, v[134:135]
	v_lshl_add_u64 v[138:139], v[142:143], 0, v[136:137]
	v_lshl_add_u64 v[136:137], v[144:145], 0, v[136:137]
	global_store_dword v[138:139], v131, off
	global_store_dword v[136:137], v133, off

.LBB0_212:
	s_or_b64 exec, exec, s[12:13]
	v_add_u32_e32 v150, 16, v140
	v_add_u32_e32 v142, 0xffffe010, v140
	v_mov_b32_e32 v143, v129
	v_lshlrev_b64 v[144:145], 8, v[142:143]
	v_ashrrev_i32_e32 v151, 31, v150
	v_lshrrev_b32_e32 v131, 5, v142
	v_or_b32_e32 v141, 16, v155
	v_lshl_add_u64 v[148:149], s[30:31], 0, v[144:145]
	v_lshlrev_b64 v[144:145], 8, v[150:151]
	v_mad_u64_u32 v[142:143], s[0:1], v131, s66, 0
	v_lshl_add_u64 v[160:161], s[58:59], 0, v[144:145]
	v_lshlrev_b64 v[144:145], 7, v[150:151]
	v_or_b32_e32 v142, v142, v141
	s_mov_b64 s[0:1], 0x1000
	v_lshl_add_u64 v[146:147], s[64:65], 0, v[144:145]
	v_lshl_add_u64 v[142:143], v[142:143], 0, s[0:1]
	v_mov_b64_e32 v[144:145], s[50:51]
	v_mad_u64_u32 v[144:145], s[0:1], v142, s67, v[144:145]
	v_and_b32_e32 v128, 0xfdf, v150
	v_or_b32_e32 v159, 0x1010, v155
	v_cmp_gt_i32_e32 vcc, s23, v150
	v_mad_u32_u24 v145, v143, s67, v145
	s_mov_b64 s[0:1], 0x131edb00
	v_cndmask_b32_e32 v128, v159, v128, vcc
	v_lshl_add_u64 v[142:143], v[144:145], 0, s[0:1]
	s_mov_b64 s[0:1], 0x131edb40
	v_lshlrev_b32_e32 v128, 5, v128
	v_cmp_lt_i32_e64 s[12:13], s56, v150
	v_lshl_add_u64 v[144:145], v[144:145], 0, s[0:1]
	v_cndmask_b32_e32 v149, v149, v161, vcc
	v_cndmask_b32_e32 v148, v148, v160, vcc
	s_and_saveexec_b64 s[0:1], s[4:5]
	s_xor_b64 vcc, exec, s[0:1]
	s_cbranch_execz .LBB0_216
	v_ashrrev_i32_e32 v133, 31, v132
	v_lshl_add_u64 v[160:161], v[128:129], 0, v[132:133]
	v_lshl_add_u64 v[160:161], v[160:161], 3, s[16:17]
	v_mov_b64_e32 v[160:161], v[180:181]
	v_mov_b64_e32 v[162:163], v[182:183]
	v_mov_b32_e32 v170, v100
	v_mov_b32_e32 v171, v103
	v_pk_mul_f32 v[164:165], v[102:103], v[162:163]
	v_pk_mul_f32 v[166:167], v[100:101], v[160:161]
	v_mov_b32_e32 v169, v164
	v_mov_b32_e32 v168, v166
	v_mov_b32_e32 v164, v167
	v_pk_add_f32 v[164:165], v[168:169], v[164:165] neg_lo:[0,1] neg_hi:[0,1]
	v_mov_b32_e32 v168, v160
	v_mov_b32_e32 v160, v161
	v_mov_b32_e32 v161, v162
	v_mov_b32_e32 v166, v101
	v_mov_b32_e32 v167, v102
	v_mov_b32_e32 v169, v163
	v_pk_mul_f32 v[160:161], v[170:171], v[160:161]
	v_lshl_add_u64 v[162:163], v[132:133], 2, v[148:149]
	v_pk_fma_f32 v[160:161], v[166:167], v[168:169], v[160:161]
	global_store_dwordx2 v[162:163], v[164:165], off
	global_store_dwordx2 v[162:163], v[160:161], off offset:128
	v_cvt_pk_bf16_f32 v131, v164, v165
	v_cvt_pk_bf16_f32 v135, v160, v161
	v_lshl_add_u64 v[160:161], v[132:133], 1, v[146:147]
	global_store_dword v[160:161], v131, off
	global_store_dword v[160:161], v135, off offset:64
	s_and_saveexec_b64 s[74:75], s[12:13]
	s_cbranch_execz .LBB0_215
	v_lshlrev_b64 v[160:161], 1, v[132:133]
	v_lshl_add_u64 v[162:163], v[142:143], 0, v[160:161]
	v_lshl_add_u64 v[160:161], v[144:145], 0, v[160:161]
	global_store_dword v[162:163], v131, off
	global_store_dword v[160:161], v135, off

.LBB0_231:
	v_ashrrev_i32_e32 v135, 31, v134
	v_lshl_add_u64 v[160:161], v[128:129], 0, v[134:135]
	v_lshl_add_u64 v[160:161], v[160:161], 3, s[16:17]
	v_mov_b64_e32 v[160:161], v[184:185]
	v_mov_b64_e32 v[162:163], v[186:187]
	v_mov_b32_e32 v170, v96
	v_mov_b32_e32 v171, v99
	v_pk_mul_f32 v[164:165], v[98:99], v[162:163]
	v_pk_mul_f32 v[166:167], v[96:97], v[160:161]
	v_mov_b32_e32 v169, v164
	v_mov_b32_e32 v168, v166
	v_mov_b32_e32 v164, v167
	v_pk_add_f32 v[164:165], v[168:169], v[164:165] neg_lo:[0,1] neg_hi:[0,1]
	v_mov_b32_e32 v168, v160
	v_mov_b32_e32 v160, v161
	v_mov_b32_e32 v161, v162
	v_mov_b32_e32 v166, v97
	v_mov_b32_e32 v167, v98
	v_mov_b32_e32 v169, v163
	v_pk_mul_f32 v[160:161], v[170:171], v[160:161]
	v_lshl_add_u64 v[162:163], v[134:135], 2, v[148:149]
	v_pk_fma_f32 v[160:161], v[166:167], v[168:169], v[160:161]
	global_store_dwordx2 v[162:163], v[164:165], off
	global_store_dwordx2 v[162:163], v[160:161], off offset:128
	v_cvt_pk_bf16_f32 v131, v164, v165
	v_cvt_pk_bf16_f32 v133, v160, v161
	v_lshl_add_u64 v[160:161], v[134:135], 1, v[146:147]
	global_store_dword v[160:161], v131, off
	global_store_dword v[160:161], v133, off offset:64
	s_and_saveexec_b64 s[74:75], s[12:13]
	s_cbranch_execz .LBB0_233
	v_lshlrev_b64 v[160:161], 1, v[134:135]
	v_lshl_add_u64 v[162:163], v[142:143], 0, v[160:161]
	v_lshl_add_u64 v[160:161], v[144:145], 0, v[160:161]
	global_store_dword v[162:163], v131, off
	global_store_dword v[160:161], v133, off

.LBB0_245:
	s_or_b64 exec, exec, s[12:13]
	v_add_u32_e32 v150, 32, v140
	v_add_u32_e32 v142, 0xffffe020, v140
	v_mov_b32_e32 v143, v129
	v_lshlrev_b64 v[144:145], 8, v[142:143]
	v_ashrrev_i32_e32 v151, 31, v150
	v_lshrrev_b32_e32 v131, 5, v142
	v_lshl_add_u64 v[148:149], s[30:31], 0, v[144:145]
	v_lshlrev_b64 v[144:145], 8, v[150:151]
	v_mad_u64_u32 v[142:143], s[0:1], v131, s66, 0
	v_lshl_add_u64 v[160:161], s[58:59], 0, v[144:145]
	v_lshlrev_b64 v[144:145], 7, v[150:151]
	v_or_b32_e32 v142, v142, v155
	s_mov_b64 s[0:1], 0x1000
	v_lshl_add_u64 v[146:147], s[64:65], 0, v[144:145]
	v_lshl_add_u64 v[142:143], v[142:143], 0, s[0:1]
	v_mov_b64_e32 v[144:145], s[50:51]
	v_mad_u64_u32 v[144:145], s[0:1], v142, s67, v[144:145]
	v_and_b32_e32 v128, 0xfef, v150
	v_cmp_gt_i32_e32 vcc, s23, v150
	v_mad_u32_u24 v145, v143, s67, v145
	s_mov_b64 s[0:1], 0x131edb00
	v_cndmask_b32_e32 v128, v158, v128, vcc
	v_lshl_add_u64 v[142:143], v[144:145], 0, s[0:1]
	s_mov_b64 s[0:1], 0x131edb40
	v_lshlrev_b32_e32 v128, 5, v128
	v_cmp_lt_i32_e64 s[12:13], s56, v150
	v_lshl_add_u64 v[144:145], v[144:145], 0, s[0:1]
	v_cndmask_b32_e32 v149, v149, v161, vcc
	v_cndmask_b32_e32 v148, v148, v160, vcc
	s_and_saveexec_b64 s[0:1], s[4:5]
	s_xor_b64 vcc, exec, s[0:1]
	s_cbranch_execz .LBB0_249
	v_ashrrev_i32_e32 v133, 31, v132
	v_lshl_add_u64 v[160:161], v[128:129], 0, v[132:133]
	v_lshl_add_u64 v[160:161], v[160:161], 3, s[16:17]
	v_mov_b64_e32 v[160:161], v[188:189]
	v_mov_b64_e32 v[162:163], v[190:191]
	v_mov_b32_e32 v170, v84
	v_mov_b32_e32 v171, v87
	v_pk_mul_f32 v[164:165], v[86:87], v[162:163]
	v_pk_mul_f32 v[166:167], v[84:85], v[160:161]
	v_mov_b32_e32 v169, v164
	v_mov_b32_e32 v168, v166
	v_mov_b32_e32 v164, v167
	v_pk_add_f32 v[164:165], v[168:169], v[164:165] neg_lo:[0,1] neg_hi:[0,1]
	v_mov_b32_e32 v168, v160
	v_mov_b32_e32 v160, v161
	v_mov_b32_e32 v161, v162
	v_mov_b32_e32 v166, v85
	v_mov_b32_e32 v167, v86
	v_mov_b32_e32 v169, v163
	v_pk_mul_f32 v[160:161], v[170:171], v[160:161]
	v_lshl_add_u64 v[162:163], v[132:133], 2, v[148:149]
	v_pk_fma_f32 v[160:161], v[166:167], v[168:169], v[160:161]
	global_store_dwordx2 v[162:163], v[164:165], off
	global_store_dwordx2 v[162:163], v[160:161], off offset:128
	v_cvt_pk_bf16_f32 v131, v164, v165
	v_cvt_pk_bf16_f32 v135, v160, v161
	v_lshl_add_u64 v[160:161], v[132:133], 1, v[146:147]
	global_store_dword v[160:161], v131, off
	global_store_dword v[160:161], v135, off offset:64
	s_and_saveexec_b64 s[74:75], s[12:13]
	s_cbranch_execz .LBB0_248
	v_lshlrev_b64 v[160:161], 1, v[132:133]
	v_lshl_add_u64 v[162:163], v[142:143], 0, v[160:161]
	v_lshl_add_u64 v[160:161], v[144:145], 0, v[160:161]
	global_store_dword v[162:163], v131, off
	global_store_dword v[160:161], v135, off

.LBB0_263:
	v_ashrrev_i32_e32 v135, 31, v134
	v_lshl_add_u64 v[160:161], v[128:129], 0, v[134:135]
	v_lshl_add_u64 v[160:161], v[160:161], 3, s[16:17]
	v_mov_b64_e32 v[160:161], v[192:193]
	v_mov_b64_e32 v[162:163], v[194:195]
	v_mov_b32_e32 v170, v80
	v_mov_b32_e32 v171, v83
	v_pk_mul_f32 v[164:165], v[82:83], v[162:163]
	v_pk_mul_f32 v[166:167], v[80:81], v[160:161]
	v_mov_b32_e32 v169, v164
	v_mov_b32_e32 v168, v166
	v_mov_b32_e32 v164, v167
	v_pk_add_f32 v[164:165], v[168:169], v[164:165] neg_lo:[0,1] neg_hi:[0,1]
	v_mov_b32_e32 v168, v160
	v_mov_b32_e32 v160, v161
	v_mov_b32_e32 v161, v162
	v_mov_b32_e32 v166, v81
	v_mov_b32_e32 v167, v82
	v_mov_b32_e32 v169, v163
	v_pk_mul_f32 v[160:161], v[170:171], v[160:161]
	v_lshl_add_u64 v[162:163], v[134:135], 2, v[148:149]
	v_pk_fma_f32 v[160:161], v[166:167], v[168:169], v[160:161]
	global_store_dwordx2 v[162:163], v[164:165], off
	global_store_dwordx2 v[162:163], v[160:161], off offset:128
	v_cvt_pk_bf16_f32 v131, v164, v165
	v_cvt_pk_bf16_f32 v133, v160, v161
	v_lshl_add_u64 v[160:161], v[134:135], 1, v[146:147]
	global_store_dword v[160:161], v131, off
	global_store_dword v[160:161], v133, off offset:64
	s_and_saveexec_b64 s[74:75], s[12:13]
	s_cbranch_execz .LBB0_265
	v_lshlrev_b64 v[160:161], 1, v[134:135]
	v_lshl_add_u64 v[162:163], v[142:143], 0, v[160:161]
	v_lshl_add_u64 v[160:161], v[144:145], 0, v[160:161]
	global_store_dword v[162:163], v131, off
	global_store_dword v[160:161], v133, off

.LBB0_277:
	s_or_b64 exec, exec, s[12:13]
	v_add_u32_e32 v150, 48, v140
	v_add_u32_e32 v142, 0xffffe030, v140
	v_mov_b32_e32 v143, v129
	v_lshlrev_b64 v[144:145], 8, v[142:143]
	v_ashrrev_i32_e32 v151, 31, v150
	v_lshrrev_b32_e32 v131, 5, v142
	v_lshl_add_u64 v[148:149], s[30:31], 0, v[144:145]
	v_lshlrev_b64 v[144:145], 8, v[150:151]
	v_mad_u64_u32 v[142:143], s[0:1], v131, s66, 0
	v_lshl_add_u64 v[160:161], s[58:59], 0, v[144:145]
	v_lshlrev_b64 v[144:145], 7, v[150:151]
	v_or_b32_e32 v142, v142, v141
	s_mov_b64 s[0:1], 0x1000
	v_lshl_add_u64 v[146:147], s[64:65], 0, v[144:145]
	v_lshl_add_u64 v[142:143], v[142:143], 0, s[0:1]
	v_mov_b64_e32 v[144:145], s[50:51]
	v_mad_u64_u32 v[144:145], s[0:1], v142, s67, v[144:145]
	v_and_b32_e32 v128, 0xfff, v150
	v_cmp_gt_i32_e32 vcc, s23, v150
	v_mad_u32_u24 v145, v143, s67, v145
	s_mov_b64 s[0:1], 0x131edb00
	v_cndmask_b32_e32 v128, v159, v128, vcc
	v_lshl_add_u64 v[142:143], v[144:145], 0, s[0:1]
	s_mov_b64 s[0:1], 0x131edb40
	v_lshlrev_b32_e32 v128, 5, v128
	v_cmp_lt_i32_e64 s[12:13], s56, v150
	v_lshl_add_u64 v[144:145], v[144:145], 0, s[0:1]
	v_cndmask_b32_e32 v149, v149, v161, vcc
	v_cndmask_b32_e32 v148, v148, v160, vcc
	s_and_saveexec_b64 s[0:1], s[4:5]
	s_xor_b64 vcc, exec, s[0:1]
	s_cbranch_execz .LBB0_281
	v_ashrrev_i32_e32 v133, 31, v132
	v_lshl_add_u64 v[160:161], v[128:129], 0, v[132:133]
	v_lshl_add_u64 v[160:161], v[160:161], 3, s[16:17]
	v_mov_b64_e32 v[160:161], v[196:197]
	v_mov_b64_e32 v[162:163], v[198:199]
	v_mov_b32_e32 v170, v60
	v_mov_b32_e32 v171, v63
	v_pk_mul_f32 v[164:165], v[62:63], v[162:163]
	v_pk_mul_f32 v[166:167], v[60:61], v[160:161]
	v_mov_b32_e32 v169, v164
	v_mov_b32_e32 v168, v166
	v_mov_b32_e32 v164, v167
	v_pk_add_f32 v[164:165], v[168:169], v[164:165] neg_lo:[0,1] neg_hi:[0,1]
	v_mov_b32_e32 v168, v160
	v_mov_b32_e32 v160, v161
	v_mov_b32_e32 v161, v162
	v_mov_b32_e32 v166, v61
	v_mov_b32_e32 v167, v62
	v_mov_b32_e32 v169, v163
	v_pk_mul_f32 v[160:161], v[170:171], v[160:161]
	v_lshl_add_u64 v[162:163], v[132:133], 2, v[148:149]
	v_pk_fma_f32 v[160:161], v[166:167], v[168:169], v[160:161]
	global_store_dwordx2 v[162:163], v[164:165], off
	global_store_dwordx2 v[162:163], v[160:161], off offset:128
	v_cvt_pk_bf16_f32 v131, v164, v165
	v_cvt_pk_bf16_f32 v135, v160, v161
	v_lshl_add_u64 v[160:161], v[132:133], 1, v[146:147]
	global_store_dword v[160:161], v131, off
	global_store_dword v[160:161], v135, off offset:64
	s_and_saveexec_b64 s[74:75], s[12:13]
	s_cbranch_execz .LBB0_280
	v_lshlrev_b64 v[160:161], 1, v[132:133]
	v_lshl_add_u64 v[162:163], v[142:143], 0, v[160:161]
	v_lshl_add_u64 v[160:161], v[144:145], 0, v[160:161]
	global_store_dword v[162:163], v131, off
	global_store_dword v[160:161], v135, off

.LBB0_295:
	v_ashrrev_i32_e32 v135, 31, v134
	v_lshl_add_u64 v[160:161], v[128:129], 0, v[134:135]
	v_lshl_add_u64 v[160:161], v[160:161], 3, s[16:17]
	v_mov_b64_e32 v[160:161], v[200:201]
	v_mov_b64_e32 v[162:163], v[202:203]
	v_mov_b32_e32 v170, v48
	v_mov_b32_e32 v171, v51
	v_pk_mul_f32 v[164:165], v[50:51], v[162:163]
	v_pk_mul_f32 v[166:167], v[48:49], v[160:161]
	v_mov_b32_e32 v169, v164
	v_mov_b32_e32 v168, v166
	v_mov_b32_e32 v164, v167
	v_pk_add_f32 v[164:165], v[168:169], v[164:165] neg_lo:[0,1] neg_hi:[0,1]
	v_mov_b32_e32 v168, v160
	v_mov_b32_e32 v160, v161
	v_mov_b32_e32 v161, v162
	v_mov_b32_e32 v166, v49
	v_mov_b32_e32 v167, v50
	v_mov_b32_e32 v169, v163
	v_pk_mul_f32 v[160:161], v[170:171], v[160:161]
	v_lshl_add_u64 v[162:163], v[134:135], 2, v[148:149]
	v_pk_fma_f32 v[160:161], v[166:167], v[168:169], v[160:161]
	global_store_dwordx2 v[162:163], v[164:165], off
	global_store_dwordx2 v[162:163], v[160:161], off offset:128
	v_cvt_pk_bf16_f32 v131, v164, v165
	v_cvt_pk_bf16_f32 v133, v160, v161
	v_lshl_add_u64 v[160:161], v[134:135], 1, v[146:147]
	global_store_dword v[160:161], v131, off
	global_store_dword v[160:161], v133, off offset:64
	s_and_saveexec_b64 s[74:75], s[12:13]
	s_cbranch_execz .LBB0_297
	v_lshlrev_b64 v[160:161], 1, v[134:135]
	v_lshl_add_u64 v[162:163], v[142:143], 0, v[160:161]
	v_lshl_add_u64 v[160:161], v[144:145], 0, v[160:161]
	global_store_dword v[162:163], v131, off
	global_store_dword v[160:161], v133, off

.LBB0_309:
	s_or_b64 exec, exec, s[12:13]
	v_add_u32_e32 v150, 0x80, v140
	v_add_u32_e32 v142, 0xffffe080, v140
	v_mov_b32_e32 v143, v129
	v_lshlrev_b64 v[144:145], 8, v[142:143]
	v_ashrrev_i32_e32 v151, 31, v150
	v_lshrrev_b32_e32 v131, 5, v142
	v_lshl_add_u64 v[148:149], s[30:31], 0, v[144:145]
	v_lshlrev_b64 v[144:145], 8, v[150:151]
	v_mad_u64_u32 v[142:143], s[0:1], v131, s66, 0
	v_lshl_add_u64 v[160:161], s[58:59], 0, v[144:145]
	v_lshlrev_b64 v[144:145], 7, v[150:151]
	v_or_b32_e32 v142, v142, v155
	s_mov_b64 s[0:1], 0x1000
	v_lshl_add_u64 v[146:147], s[64:65], 0, v[144:145]
	v_lshl_add_u64 v[142:143], v[142:143], 0, s[0:1]
	v_mov_b64_e32 v[144:145], s[50:51]
	v_mad_u64_u32 v[144:145], s[0:1], v142, s67, v[144:145]
	v_and_b32_e32 v128, 0xfcf, v150
	v_cmp_gt_i32_e32 vcc, s23, v150
	v_mad_u32_u24 v145, v143, s67, v145
	s_mov_b64 s[0:1], 0x131edb00
	v_cndmask_b32_e32 v128, v158, v128, vcc
	v_lshl_add_u64 v[142:143], v[144:145], 0, s[0:1]
	s_mov_b64 s[0:1], 0x131edb40
	v_lshlrev_b32_e32 v128, 5, v128
	v_cmp_lt_i32_e64 s[12:13], s56, v150
	v_lshl_add_u64 v[144:145], v[144:145], 0, s[0:1]
	v_cndmask_b32_e32 v149, v149, v161, vcc
	v_cndmask_b32_e32 v148, v148, v160, vcc
	s_and_saveexec_b64 s[0:1], s[4:5]
	s_xor_b64 vcc, exec, s[0:1]
	s_cbranch_execz .LBB0_313
	v_ashrrev_i32_e32 v133, 31, v132
	v_lshl_add_u64 v[160:161], v[128:129], 0, v[132:133]
	v_lshl_add_u64 v[160:161], v[160:161], 3, s[16:17]
	v_mov_b64_e32 v[160:161], v[204:205]
	v_mov_b64_e32 v[162:163], v[206:207]
	v_mov_b32_e32 v170, v72
	v_mov_b32_e32 v171, v75
	v_pk_mul_f32 v[164:165], v[74:75], v[162:163]
	v_pk_mul_f32 v[166:167], v[72:73], v[160:161]
	v_mov_b32_e32 v169, v164
	v_mov_b32_e32 v168, v166
	v_mov_b32_e32 v164, v167
	v_pk_add_f32 v[164:165], v[168:169], v[164:165] neg_lo:[0,1] neg_hi:[0,1]
	v_mov_b32_e32 v168, v160
	v_mov_b32_e32 v160, v161
	v_mov_b32_e32 v161, v162
	v_mov_b32_e32 v166, v73
	v_mov_b32_e32 v167, v74
	v_mov_b32_e32 v169, v163
	v_pk_mul_f32 v[160:161], v[170:171], v[160:161]
	v_lshl_add_u64 v[162:163], v[132:133], 2, v[148:149]
	v_pk_fma_f32 v[160:161], v[166:167], v[168:169], v[160:161]
	global_store_dwordx2 v[162:163], v[164:165], off
	global_store_dwordx2 v[162:163], v[160:161], off offset:128
	v_cvt_pk_bf16_f32 v131, v164, v165
	v_cvt_pk_bf16_f32 v135, v160, v161
	v_lshl_add_u64 v[160:161], v[132:133], 1, v[146:147]
	global_store_dword v[160:161], v131, off
	global_store_dword v[160:161], v135, off offset:64
	s_and_saveexec_b64 s[74:75], s[12:13]
	s_cbranch_execz .LBB0_312
	v_lshlrev_b64 v[160:161], 1, v[132:133]
	v_lshl_add_u64 v[162:163], v[142:143], 0, v[160:161]
	v_lshl_add_u64 v[160:161], v[144:145], 0, v[160:161]
	global_store_dword v[162:163], v131, off
	global_store_dword v[160:161], v135, off

.LBB0_327:
	v_ashrrev_i32_e32 v135, 31, v134
	v_lshl_add_u64 v[160:161], v[128:129], 0, v[134:135]
	v_lshl_add_u64 v[160:161], v[160:161], 3, s[16:17]
	v_mov_b64_e32 v[160:161], v[208:209]
	v_mov_b64_e32 v[162:163], v[210:211]
	v_mov_b32_e32 v170, v52
	v_mov_b32_e32 v171, v55
	v_pk_mul_f32 v[164:165], v[54:55], v[162:163]
	v_pk_mul_f32 v[166:167], v[52:53], v[160:161]
	v_mov_b32_e32 v169, v164
	v_mov_b32_e32 v168, v166
	v_mov_b32_e32 v164, v167
	v_pk_add_f32 v[164:165], v[168:169], v[164:165] neg_lo:[0,1] neg_hi:[0,1]
	v_mov_b32_e32 v168, v160
	v_mov_b32_e32 v160, v161
	v_mov_b32_e32 v161, v162
	v_mov_b32_e32 v166, v53
	v_mov_b32_e32 v167, v54
	v_mov_b32_e32 v169, v163
	v_pk_mul_f32 v[160:161], v[170:171], v[160:161]
	v_lshl_add_u64 v[162:163], v[134:135], 2, v[148:149]
	v_pk_fma_f32 v[160:161], v[166:167], v[168:169], v[160:161]
	global_store_dwordx2 v[162:163], v[164:165], off
	global_store_dwordx2 v[162:163], v[160:161], off offset:128
	v_cvt_pk_bf16_f32 v131, v164, v165
	v_cvt_pk_bf16_f32 v133, v160, v161
	v_lshl_add_u64 v[160:161], v[134:135], 1, v[146:147]
	global_store_dword v[160:161], v131, off
	global_store_dword v[160:161], v133, off offset:64
	s_and_saveexec_b64 s[74:75], s[12:13]
	s_cbranch_execz .LBB0_329
	v_lshlrev_b64 v[160:161], 1, v[134:135]
	v_lshl_add_u64 v[162:163], v[142:143], 0, v[160:161]
	v_lshl_add_u64 v[160:161], v[144:145], 0, v[160:161]
	global_store_dword v[162:163], v131, off
	global_store_dword v[160:161], v133, off

.LBB0_341:
	s_or_b64 exec, exec, s[12:13]
	v_add_u32_e32 v150, 0x90, v140
	v_add_u32_e32 v142, 0xffffe090, v140
	v_mov_b32_e32 v143, v129
	v_lshlrev_b64 v[144:145], 8, v[142:143]
	v_ashrrev_i32_e32 v151, 31, v150
	v_lshrrev_b32_e32 v131, 5, v142
	v_lshl_add_u64 v[148:149], s[30:31], 0, v[144:145]
	v_lshlrev_b64 v[144:145], 8, v[150:151]
	v_mad_u64_u32 v[142:143], s[0:1], v131, s66, 0
	v_lshl_add_u64 v[160:161], s[58:59], 0, v[144:145]
	v_lshlrev_b64 v[144:145], 7, v[150:151]
	v_or_b32_e32 v142, v142, v141
	s_mov_b64 s[0:1], 0x1000
	v_lshl_add_u64 v[146:147], s[64:65], 0, v[144:145]
	v_lshl_add_u64 v[142:143], v[142:143], 0, s[0:1]
	v_mov_b64_e32 v[144:145], s[50:51]
	v_mad_u64_u32 v[144:145], s[0:1], v142, s67, v[144:145]
	v_and_b32_e32 v128, 0xfdf, v150
	v_cmp_gt_i32_e32 vcc, s23, v150
	v_mad_u32_u24 v145, v143, s67, v145
	s_mov_b64 s[0:1], 0x131edb00
	v_cndmask_b32_e32 v128, v159, v128, vcc
	v_lshl_add_u64 v[142:143], v[144:145], 0, s[0:1]
	s_mov_b64 s[0:1], 0x131edb40
	v_lshlrev_b32_e32 v128, 5, v128
	v_cmp_lt_i32_e64 s[12:13], s56, v150
	v_lshl_add_u64 v[144:145], v[144:145], 0, s[0:1]
	v_cndmask_b32_e32 v149, v149, v161, vcc
	v_cndmask_b32_e32 v148, v148, v160, vcc
	s_and_saveexec_b64 s[0:1], s[4:5]
	s_xor_b64 vcc, exec, s[0:1]
	s_cbranch_execz .LBB0_345
	v_ashrrev_i32_e32 v133, 31, v132
	v_lshl_add_u64 v[160:161], v[128:129], 0, v[132:133]
	v_lshl_add_u64 v[160:161], v[160:161], 3, s[16:17]
	v_mov_b64_e32 v[160:161], v[212:213]
	v_mov_b64_e32 v[162:163], v[214:215]
	v_mov_b32_e32 v170, v44
	v_mov_b32_e32 v171, v47
	v_pk_mul_f32 v[164:165], v[46:47], v[162:163]
	v_pk_mul_f32 v[166:167], v[44:45], v[160:161]
	v_mov_b32_e32 v169, v164
	v_mov_b32_e32 v168, v166
	v_mov_b32_e32 v164, v167
	v_pk_add_f32 v[164:165], v[168:169], v[164:165] neg_lo:[0,1] neg_hi:[0,1]
	v_mov_b32_e32 v168, v160
	v_mov_b32_e32 v160, v161
	v_mov_b32_e32 v161, v162
	v_mov_b32_e32 v166, v45
	v_mov_b32_e32 v167, v46
	v_mov_b32_e32 v169, v163
	v_pk_mul_f32 v[160:161], v[170:171], v[160:161]
	v_lshl_add_u64 v[162:163], v[132:133], 2, v[148:149]
	v_pk_fma_f32 v[160:161], v[166:167], v[168:169], v[160:161]
	global_store_dwordx2 v[162:163], v[164:165], off
	global_store_dwordx2 v[162:163], v[160:161], off offset:128
	v_cvt_pk_bf16_f32 v131, v164, v165
	v_cvt_pk_bf16_f32 v135, v160, v161
	v_lshl_add_u64 v[160:161], v[132:133], 1, v[146:147]
	global_store_dword v[160:161], v131, off
	global_store_dword v[160:161], v135, off offset:64
	s_and_saveexec_b64 s[74:75], s[12:13]
	s_cbranch_execz .LBB0_344
	v_lshlrev_b64 v[160:161], 1, v[132:133]
	v_lshl_add_u64 v[162:163], v[142:143], 0, v[160:161]
	v_lshl_add_u64 v[160:161], v[144:145], 0, v[160:161]
	global_store_dword v[162:163], v131, off
	global_store_dword v[160:161], v135, off

.LBB0_359:
	v_ashrrev_i32_e32 v135, 31, v134
	v_lshl_add_u64 v[160:161], v[128:129], 0, v[134:135]
	v_lshl_add_u64 v[160:161], v[160:161], 3, s[16:17]
	v_mov_b64_e32 v[160:161], v[216:217]
	v_mov_b64_e32 v[162:163], v[218:219]
	v_mov_b32_e32 v170, v32
	v_mov_b32_e32 v171, v35
	v_pk_mul_f32 v[164:165], v[34:35], v[162:163]
	v_pk_mul_f32 v[166:167], v[32:33], v[160:161]
	v_mov_b32_e32 v169, v164
	v_mov_b32_e32 v168, v166
	v_mov_b32_e32 v164, v167
	v_pk_add_f32 v[164:165], v[168:169], v[164:165] neg_lo:[0,1] neg_hi:[0,1]
	v_mov_b32_e32 v168, v160
	v_mov_b32_e32 v160, v161
	v_mov_b32_e32 v161, v162
	v_mov_b32_e32 v166, v33
	v_mov_b32_e32 v167, v34
	v_mov_b32_e32 v169, v163
	v_pk_mul_f32 v[160:161], v[170:171], v[160:161]
	v_lshl_add_u64 v[162:163], v[134:135], 2, v[148:149]
	v_pk_fma_f32 v[160:161], v[166:167], v[168:169], v[160:161]
	global_store_dwordx2 v[162:163], v[164:165], off
	global_store_dwordx2 v[162:163], v[160:161], off offset:128
	v_cvt_pk_bf16_f32 v131, v164, v165
	v_cvt_pk_bf16_f32 v133, v160, v161
	v_lshl_add_u64 v[160:161], v[134:135], 1, v[146:147]
	global_store_dword v[160:161], v131, off
	global_store_dword v[160:161], v133, off offset:64
	s_and_saveexec_b64 s[74:75], s[12:13]
	s_cbranch_execz .LBB0_361
	v_lshlrev_b64 v[160:161], 1, v[134:135]
	v_lshl_add_u64 v[162:163], v[142:143], 0, v[160:161]
	v_lshl_add_u64 v[160:161], v[144:145], 0, v[160:161]
	global_store_dword v[162:163], v131, off
	global_store_dword v[160:161], v133, off

.LBB0_373:
	s_or_b64 exec, exec, s[12:13]
	v_add_u32_e32 v150, 0xa0, v140
	v_add_u32_e32 v142, 0xffffe0a0, v140
	v_mov_b32_e32 v143, v129
	v_lshlrev_b64 v[144:145], 8, v[142:143]
	v_ashrrev_i32_e32 v151, 31, v150
	v_lshrrev_b32_e32 v131, 5, v142
	v_lshl_add_u64 v[148:149], s[30:31], 0, v[144:145]
	v_lshlrev_b64 v[144:145], 8, v[150:151]
	v_mad_u64_u32 v[142:143], s[0:1], v131, s66, 0
	v_lshl_add_u64 v[160:161], s[58:59], 0, v[144:145]
	v_lshlrev_b64 v[144:145], 7, v[150:151]
	v_or_b32_e32 v142, v142, v155
	s_mov_b64 s[0:1], 0x1000
	v_lshl_add_u64 v[146:147], s[64:65], 0, v[144:145]
	v_lshl_add_u64 v[142:143], v[142:143], 0, s[0:1]
	v_mov_b64_e32 v[144:145], s[50:51]
	v_mad_u64_u32 v[144:145], s[0:1], v142, s67, v[144:145]
	v_and_b32_e32 v128, 0xfef, v150
	v_cmp_gt_i32_e32 vcc, s23, v150
	v_mad_u32_u24 v145, v143, s67, v145
	s_mov_b64 s[0:1], 0x131edb00
	v_cndmask_b32_e32 v128, v158, v128, vcc
	v_lshl_add_u64 v[142:143], v[144:145], 0, s[0:1]
	s_mov_b64 s[0:1], 0x131edb40
	v_lshlrev_b32_e32 v128, 5, v128
	v_cmp_lt_i32_e64 s[12:13], s56, v150
	v_lshl_add_u64 v[144:145], v[144:145], 0, s[0:1]
	v_cndmask_b32_e32 v149, v149, v161, vcc
	v_cndmask_b32_e32 v148, v148, v160, vcc
	s_and_saveexec_b64 s[0:1], s[4:5]
	s_xor_b64 vcc, exec, s[0:1]
	s_cbranch_execz .LBB0_377
	v_ashrrev_i32_e32 v133, 31, v132
	v_lshl_add_u64 v[160:161], v[128:129], 0, v[132:133]
	v_lshl_add_u64 v[160:161], v[160:161], 3, s[16:17]
	v_mov_b64_e32 v[160:161], v[220:221]
	v_mov_b64_e32 v[162:163], v[222:223]
	v_mov_b32_e32 v170, v28
	v_mov_b32_e32 v171, v31
	v_pk_mul_f32 v[164:165], v[30:31], v[162:163]
	v_pk_mul_f32 v[166:167], v[28:29], v[160:161]
	v_mov_b32_e32 v169, v164
	v_mov_b32_e32 v168, v166
	v_mov_b32_e32 v164, v167
	v_pk_add_f32 v[164:165], v[168:169], v[164:165] neg_lo:[0,1] neg_hi:[0,1]
	v_mov_b32_e32 v168, v160
	v_mov_b32_e32 v160, v161
	v_mov_b32_e32 v161, v162
	v_mov_b32_e32 v166, v29
	v_mov_b32_e32 v167, v30
	v_mov_b32_e32 v169, v163
	v_pk_mul_f32 v[160:161], v[170:171], v[160:161]
	v_lshl_add_u64 v[162:163], v[132:133], 2, v[148:149]
	v_pk_fma_f32 v[160:161], v[166:167], v[168:169], v[160:161]
	global_store_dwordx2 v[162:163], v[164:165], off
	global_store_dwordx2 v[162:163], v[160:161], off offset:128
	v_cvt_pk_bf16_f32 v131, v164, v165
	v_cvt_pk_bf16_f32 v135, v160, v161
	v_lshl_add_u64 v[160:161], v[132:133], 1, v[146:147]
	global_store_dword v[160:161], v131, off
	global_store_dword v[160:161], v135, off offset:64
	s_and_saveexec_b64 s[74:75], s[12:13]
	s_cbranch_execz .LBB0_376
	v_lshlrev_b64 v[160:161], 1, v[132:133]
	v_lshl_add_u64 v[162:163], v[142:143], 0, v[160:161]
	v_lshl_add_u64 v[160:161], v[144:145], 0, v[160:161]
	global_store_dword v[162:163], v131, off
	global_store_dword v[160:161], v135, off

.LBB0_391:
	v_ashrrev_i32_e32 v135, 31, v134
	v_lshl_add_u64 v[160:161], v[128:129], 0, v[134:135]
	v_lshl_add_u64 v[160:161], v[160:161], 3, s[16:17]
	v_mov_b64_e32 v[160:161], v[224:225]
	v_mov_b64_e32 v[162:163], v[226:227]
	v_mov_b32_e32 v170, v16
	v_mov_b32_e32 v171, v19
	v_pk_mul_f32 v[164:165], v[18:19], v[162:163]
	v_pk_mul_f32 v[166:167], v[16:17], v[160:161]
	v_mov_b32_e32 v169, v164
	v_mov_b32_e32 v168, v166
	v_mov_b32_e32 v164, v167
	v_pk_add_f32 v[164:165], v[168:169], v[164:165] neg_lo:[0,1] neg_hi:[0,1]
	v_mov_b32_e32 v168, v160
	v_mov_b32_e32 v160, v161
	v_mov_b32_e32 v161, v162
	v_mov_b32_e32 v166, v17
	v_mov_b32_e32 v167, v18
	v_mov_b32_e32 v169, v163
	v_pk_mul_f32 v[160:161], v[170:171], v[160:161]
	v_lshl_add_u64 v[162:163], v[134:135], 2, v[148:149]
	v_pk_fma_f32 v[160:161], v[166:167], v[168:169], v[160:161]
	global_store_dwordx2 v[162:163], v[164:165], off
	global_store_dwordx2 v[162:163], v[160:161], off offset:128
	v_cvt_pk_bf16_f32 v131, v164, v165
	v_cvt_pk_bf16_f32 v133, v160, v161
	v_lshl_add_u64 v[160:161], v[134:135], 1, v[146:147]
	global_store_dword v[160:161], v131, off
	global_store_dword v[160:161], v133, off offset:64
	s_and_saveexec_b64 s[74:75], s[12:13]
	s_cbranch_execz .LBB0_393
	v_lshlrev_b64 v[160:161], 1, v[134:135]
	v_lshl_add_u64 v[162:163], v[142:143], 0, v[160:161]
	v_lshl_add_u64 v[160:161], v[144:145], 0, v[160:161]
	global_store_dword v[162:163], v131, off
	global_store_dword v[160:161], v133, off

.LBB0_405:
	s_or_b64 exec, exec, s[12:13]
	v_add_u32_e32 v142, 0xffffe0b0, v140
	v_mov_b32_e32 v143, v129
	v_lshrrev_b32_e32 v131, 5, v142
	v_lshlrev_b64 v[144:145], 8, v[142:143]
	v_mad_u64_u32 v[142:143], s[0:1], v131, s66, 0
	v_or_b32_e32 v142, v142, v141
	s_mov_b64 s[0:1], 0x1000
	v_add_u32_e32 v148, 0xb0, v140
	v_lshl_add_u64 v[140:141], v[142:143], 0, s[0:1]
	v_mov_b64_e32 v[142:143], s[50:51]
	v_ashrrev_i32_e32 v149, 31, v148
	v_mad_u64_u32 v[142:143], s[0:1], v140, s67, v[142:143]
	v_and_b32_e32 v128, 0xfff, v148
	v_cmp_gt_i32_e32 vcc, s23, v148
	v_lshl_add_u64 v[146:147], s[30:31], 0, v[144:145]
	v_lshlrev_b64 v[144:145], 8, v[148:149]
	v_mad_u32_u24 v143, v141, s67, v143
	s_mov_b64 s[0:1], 0x131edb00
	v_cndmask_b32_e32 v128, v159, v128, vcc
	v_lshl_add_u64 v[150:151], s[58:59], 0, v[144:145]
	v_lshlrev_b64 v[144:145], 7, v[148:149]
	v_lshl_add_u64 v[140:141], v[142:143], 0, s[0:1]
	s_mov_b64 s[0:1], 0x131edb40
	v_lshlrev_b32_e32 v128, 5, v128
	v_lshl_add_u64 v[144:145], s[64:65], 0, v[144:145]
	v_cmp_lt_i32_e64 s[12:13], s56, v148
	v_lshl_add_u64 v[142:143], v[142:143], 0, s[0:1]
	v_cndmask_b32_e32 v147, v147, v151, vcc
	v_cndmask_b32_e32 v146, v146, v150, vcc
	s_and_saveexec_b64 s[0:1], s[4:5]
	s_xor_b64 s[4:5], exec, s[0:1]
	s_cbranch_execz .LBB0_409
	v_ashrrev_i32_e32 v133, 31, v132
	v_lshl_add_u64 v[150:151], v[128:129], 0, v[132:133]
	v_lshl_add_u64 v[150:151], v[150:151], 3, s[16:17]
	v_mov_b64_e32 v[158:159], v[228:229]
	v_mov_b64_e32 v[160:161], v[230:231]
	v_mov_b32_e32 v166, v12
	v_mov_b32_e32 v167, v15
	v_pk_mul_f32 v[150:151], v[14:15], v[160:161]
	v_pk_mul_f32 v[162:163], v[12:13], v[158:159]
	v_mov_b32_e32 v165, v150
	v_mov_b32_e32 v164, v162
	v_mov_b32_e32 v150, v163
	v_pk_add_f32 v[150:151], v[164:165], v[150:151] neg_lo:[0,1] neg_hi:[0,1]
	v_mov_b32_e32 v164, v158
	v_mov_b32_e32 v158, v159
	v_mov_b32_e32 v159, v160
	v_mov_b32_e32 v162, v13
	v_mov_b32_e32 v163, v14
	v_mov_b32_e32 v165, v161
	v_pk_mul_f32 v[158:159], v[166:167], v[158:159]
	v_lshl_add_u64 v[160:161], v[132:133], 2, v[146:147]
	v_pk_fma_f32 v[158:159], v[162:163], v[164:165], v[158:159]
	global_store_dwordx2 v[160:161], v[150:151], off
	global_store_dwordx2 v[160:161], v[158:159], off offset:128
	v_cvt_pk_bf16_f32 v131, v150, v151
	v_cvt_pk_bf16_f32 v135, v158, v159
	v_lshl_add_u64 v[150:151], v[132:133], 1, v[144:145]
	global_store_dword v[150:151], v131, off
	global_store_dword v[150:151], v135, off offset:64
	s_and_saveexec_b64 s[74:75], s[12:13]
	s_cbranch_execz .LBB0_408
	v_lshlrev_b64 v[132:133], 1, v[132:133]
	v_lshl_add_u64 v[150:151], v[140:141], 0, v[132:133]
	v_lshl_add_u64 v[132:133], v[142:143], 0, v[132:133]
	global_store_dword v[150:151], v131, off
	global_store_dword v[132:133], v135, off

.LBB0_423:
	v_ashrrev_i32_e32 v135, 31, v134
	v_lshl_add_u64 v[148:149], v[128:129], 0, v[134:135]
	v_lshl_add_u64 v[148:149], v[148:149], 3, s[16:17]
	v_mov_b64_e32 v[148:149], v[232:233]
	v_mov_b64_e32 v[150:151], v[234:235]
	v_mov_b32_e32 v164, v0
	v_mov_b32_e32 v165, v3
	v_pk_mul_f32 v[158:159], v[2:3], v[150:151]
	v_pk_mul_f32 v[160:161], v[0:1], v[148:149]
	v_mov_b32_e32 v163, v158
	v_mov_b32_e32 v162, v160
	v_mov_b32_e32 v158, v161
	v_pk_add_f32 v[158:159], v[162:163], v[158:159] neg_lo:[0,1] neg_hi:[0,1]
	v_mov_b32_e32 v162, v148
	v_mov_b32_e32 v148, v149
	v_mov_b32_e32 v149, v150
	v_mov_b32_e32 v160, v1
	v_mov_b32_e32 v161, v2
	v_mov_b32_e32 v163, v151
	v_pk_mul_f32 v[148:149], v[164:165], v[148:149]
	v_lshl_add_u64 v[150:151], v[134:135], 2, v[146:147]
	v_pk_fma_f32 v[148:149], v[160:161], v[162:163], v[148:149]
	global_store_dwordx2 v[150:151], v[158:159], off
	global_store_dwordx2 v[150:151], v[148:149], off offset:128
	v_cvt_pk_bf16_f32 v131, v158, v159
	v_cvt_pk_bf16_f32 v137, v148, v149
	v_lshl_add_u64 v[148:149], v[134:135], 1, v[144:145]
	global_store_dword v[148:149], v131, off
	global_store_dword v[148:149], v137, off offset:64
	s_and_saveexec_b64 s[6:7], s[12:13]
	s_cbranch_execz .LBB0_425
	v_lshlrev_b64 v[134:135], 1, v[134:135]
	v_lshl_add_u64 v[148:149], v[140:141], 0, v[134:135]
	v_lshl_add_u64 v[134:135], v[142:143], 0, v[134:135]
	global_store_dword v[148:149], v131, off
	global_store_dword v[134:135], v137, off
